# up-proj epilogue: the eight per-row rstd values are fetched at tile start (registers idle across the K-loop) instead of in two serial round trips at the start of every epilogue
# speedup vs baseline: 1.0023x; 1.0023x over previous
;     __host__ __device__ bool next(int i, Unit& u) const {
;         const long L = (long)i * G + c; if (L >= nwg) return false;
;         int wgid = (int)L; { const int q = nwg / NXCD, r = nwg % NXCD, xcd = wgid % NXCD, off = wgid / NXCD; wgid = (xcd < r ? xcd * (q + 1) : r * (q + 1) + (xcd - r) * q) + off; }
;         const int nig = WGM * nN, gid = wgid / nig, fm = gid * WGM, gsz = (nM - fm) < WGM ? (nM - fm) : WGM;
;         u.pm = fm + ((wgid % nig) % gsz); u.pn = (wgid % nig) / gsz; return true;
;     DI void operator()(pg8::f32x4 (&acc)[2][2][4][2], const pg8::Unit& u, int wr, int wc, int fr, int fq) const {
;     ...
;                 const float rs = rstdx[u.pm * 256 + ai * 128 + wr * 64 + m * 16 + fr];
.LBB0_239:
	s_lshl_b32 s100, s24, 8
	s_add_i32 s100, s100, s2
	v_or_b32_e32 v250, s100, v170
	v_ashrrev_i32_e32 v251, 31, v250
	v_lshl_add_u64 v[248:249], v[250:251], 2, s[10:11]
	global_load_dword v238, v[248:249], off
	global_load_dword v239, v[248:249], off offset:64
	global_load_dword v242, v[248:249], off offset:128
	global_load_dword v243, v[248:249], off offset:192
	global_load_dword v244, v[248:249], off offset:512
	global_load_dword v245, v[248:249], off offset:576
	global_load_dword v246, v[248:249], off offset:640
	global_load_dword v247, v[248:249], off offset:704
	s_add_i32 s84, s84, 1
	s_mul_i32 s23, s84, s7
	s_mul_hi_u32 s25, s84, s95
	s_add_i32 s25, s25, s23
	s_mul_i32 s23, s84, s95
	s_add_u32 s30, s23, s4
	s_addc_u32 s31, s25, s5
	v_mov_b64_e32 v[0:1], 0xb00
	v_cmp_lt_i64_e64 s[40:41], s[30:31], v[0:1]
	v_mov_b64_e32 v[0:1], 0xaff
	v_cmp_gt_i64_e32 vcc, s[30:31], v[0:1]
	s_cbranch_vccnz .LBB0_241
	s_ashr_i32 s23, s30, 31
	s_lshr_b32 s23, s23, 29
	s_add_i32 s23, s30, s23
	s_ashr_i32 s25, s23, 3
	s_and_b32 s23, s23, -8
	s_sub_i32 s23, s30, s23
	s_cmp_lt_i32 s23, 0
	s_cselect_b32 s30, 0x161, s1
	s_mul_i32 s23, s23, s30
	s_add_i32 s23, s23, s25
	s_mul_hi_i32 s25, s23, 0x2e8ba2e9
	s_lshr_b32 s30, s25, 31
	s_ashr_i32 s25, s25, 5
	s_add_i32 s25, s25, s30
	s_lshl_b32 s30, s25, 3
	s_sub_i32 s31, 0x80, s30
	s_min_i32 s31, s31, 8
	s_abs_i32 s34, s31
	v_cvt_f32_u32_e32 v0, s34
	s_sub_i32 s42, 0, s34
	s_mulk_i32 s25, 0xb0
	s_sub_i32 s23, s23, s25
	v_rcp_iflag_f32_e32 v0, v0
	s_abs_i32 s25, s23
	s_xor_b32 s35, s23, s31
	s_ashr_i32 s35, s35, 31
	v_mul_f32_e32 v0, 0x4f7ffffe, v0
	v_cvt_u32_f32_e32 v0, v0
	s_nop 0
	v_readfirstlane_b32 s43, v0
	s_mul_i32 s42, s42, s43
	s_mul_hi_u32 s42, s43, s42
	s_add_i32 s43, s43, s42
	s_mul_hi_u32 s42, s25, s43
	s_mul_i32 s43, s42, s34
	s_sub_i32 s25, s25, s43
	s_add_i32 s44, s42, 1
	s_sub_i32 s43, s25, s34
	s_cmp_ge_u32 s25, s34
	s_cselect_b32 s42, s44, s42
	s_cselect_b32 s25, s43, s25
	s_add_i32 s43, s42, 1
	s_cmp_ge_u32 s25, s34
	s_cselect_b32 s25, s43, s42
	s_xor_b32 s25, s25, s35
	s_sub_i32 s48, s25, s35
	s_mul_i32 s25, s48, s31
	s_sub_i32 s23, s23, s25
	s_add_i32 s50, s30, s23

; #define LAS __attribute__((address_space(3)))
;     DI void operator()(pg8::f32x4 (&acc)[2][2][4][2], const pg8::Unit& u, int wr, int wc, int fr, int fq) const {
;         LAS v4f* H = (LAS v4f*)halo;
; #pragma unroll
;         for (int ai = 0; ai < 2; ++ai)
; #pragma unroll
;             for (int m = 0; m < 4; ++m) {
;                 const float rs = rstdx[u.pm * 256 + ai * 128 + wr * 64 + m * 16 + fr];
; #pragma unroll
;                 for (int bj = 0; bj < 2; ++bj)
; #pragma unroll
;                     for (int n = 0; n < 2; ++n) acc[ai][bj][m][n] = acc[ai][bj][m][n] * rs;
;             }
;         const int hl = (fr & 1) + 2 * fq;
;         if (fr >= 14) {
; #pragma unroll
;             for (int ai = 0; ai < 2; ++ai)
; #pragma unroll
;                 for (int bj = 0; bj < 2; ++bj)
; #pragma unroll
;                     for (int n = 0; n < 2; ++n) { const pg8::f32x4 v = acc[ai][bj][3][n]; H[(((ai * 2 + wr) * 4 + wc) * 4 + bj * 2 + n) * 8 + hl] = (v4f){v[0], v[1], v[2], v[3]}; }
;         }
.LBB0_245:
	s_lshl_b32 s34, s24, 8
	s_add_i32 s34, s34, s2
	v_or_b32_e32 v124, s34, v170
	v_ashrrev_i32_e32 v125, 31, v124
	v_lshl_add_u64 v[126:127], v[124:125], 2, s[10:11]
	v_mov_b32_e32 v122, v238
	v_mov_b32_e32 v200, v239
	v_mov_b32_e32 v198, v242
	v_mov_b32_e32 v64, v243
	v_pk_mul_f32 v[146:147], v[94:95], v[64:65] op_sel_hi:[1,0]
	v_mov_b32_e32 v196, v244
	v_mov_b32_e32 v194, v245
	v_mov_b32_e32 v192, v246
	v_pk_mul_f32 v[152:153], v[120:121], v[64:65] op_sel_hi:[1,0]
	v_pk_mul_f32 v[150:151], v[118:119], v[64:65] op_sel_hi:[1,0]
	v_pk_mul_f32 v[54:55], v[54:55], v[64:65] op_sel_hi:[1,0]
	v_pk_mul_f32 v[52:53], v[52:53], v[64:65] op_sel_hi:[1,0]
	v_pk_mul_f32 v[148:149], v[96:97], v[64:65] op_sel_hi:[1,0]
	v_pk_mul_f32 v[50:51], v[50:51], v[64:65] op_sel_hi:[1,0]
	v_pk_mul_f32 v[48:49], v[48:49], v[64:65] op_sel_hi:[1,0]
	v_mov_b32_e32 v64, v247
	v_pk_mul_f32 v[96:97], v[92:93], v[64:65] op_sel_hi:[1,0]
	v_pk_mul_f32 v[94:95], v[90:91], v[64:65] op_sel_hi:[1,0]
	v_pk_mul_f32 v[30:31], v[30:31], v[64:65] op_sel_hi:[1,0]
	v_pk_mul_f32 v[28:29], v[28:29], v[64:65] op_sel_hi:[1,0]
	v_pk_mul_f32 v[92:93], v[88:89], v[64:65] op_sel_hi:[1,0]
	v_pk_mul_f32 v[90:91], v[86:87], v[64:65] op_sel_hi:[1,0]
	v_pk_mul_f32 v[26:27], v[26:27], v[64:65] op_sel_hi:[1,0]
	v_pk_mul_f32 v[24:25], v[24:25], v[64:65] op_sel_hi:[1,0]
	s_and_saveexec_b64 s[26:27], s[38:39]
	s_movk_i32 s0, 0x1600
	s_cbranch_execz .LBB0_247
	ds_write_b128 v217, v[150:153]
	ds_write_b128 v217, v[52:55] offset:128
	ds_write_b128 v217, v[146:149] offset:256
	ds_write_b128 v217, v[48:51] offset:384
	ds_write_b128 v217, v[94:97] offset:4096
	ds_write_b128 v217, v[28:31] offset:4224
	ds_write_b128 v217, v[90:93] offset:4352
	ds_write_b128 v217, v[24:27] offset:4480
	s_or_b64 exec, exec, s[26:27]
	v_lshlrev_b32_e32 v64, 2, v184
	s_and_saveexec_b64 s[26:27], s[18:19]
	s_cbranch_execz .LBB0_249
	s_branch .LBB0_248
